# PR1: attention unit prologue de-serialised: the 4 loads of K/V tile 1 issued together with tile 0's (one vmcnt(4) wait for tile 0), on top of BE1
# speedup vs baseline: 1.0032x; 1.0032x over previous
.LBB0_626:
	v_mov_b32_e32 v4, v0
	s_lshl_b64 s[8:9], s[18:19], 12
	s_add_u32 s8, s4, s8
	v_ashrrev_i32_e32 v167, 6, v4
	v_and_b32_e32 v165, 31, v4
	v_lshlrev_b32_e32 v164, 5, v167
	s_addc_u32 s9, s5, s9
	s_lshl_b32 s18, s30, 8
	v_or_b32_e32 v6, v164, v165
	s_add_u32 s40, s8, s18
	v_ashrrev_i32_e32 v7, 31, v6
	s_addc_u32 s41, s9, 0
	v_bfe_u32 v170, v4, 5, 1
	v_lshlrev_b64 v[6:7], 12, v[6:7]
	v_lshl_add_u64 v[6:7], s[40:41], 0, v[6:7]
	v_lshlrev_b32_e32 v168, 4, v170
	v_mov_b32_e32 v169, v3
	s_lshl_b64 s[8:9], s[16:17], 10
	v_lshl_add_u64 v[6:7], v[6:7], 0, v[168:169]
	v_ashrrev_i32_e32 v5, 4, v4
	s_add_u32 s18, s14, s8
	global_load_dwordx4 v[128:131], v[6:7], off
	global_load_dwordx4 v[124:127], v[6:7], off offset:32
	global_load_dwordx4 v[120:123], v[6:7], off offset:64
	global_load_dwordx4 v[116:119], v[6:7], off offset:96
	global_load_dwordx4 v[112:115], v[6:7], off offset:128
	global_load_dwordx4 v[108:111], v[6:7], off offset:160
	global_load_dwordx4 v[104:107], v[6:7], off offset:192
	global_load_dwordx4 v[100:103], v[6:7], off offset:224
	v_and_b32_e32 v7, 0xfffff8, v5
	v_lshlrev_b32_e32 v8, 1, v5
	s_addc_u32 s19, s15, s9
	s_lshl_b64 s[16:17], s[36:37], 1
	v_lshrrev_b32_e32 v8, 1, v5
	v_and_b32_e32 v9, 3, v5
	v_add_u32_e32 v22, 32, v5
	s_add_u32 s30, s18, s16
	v_and_b32_e32 v8, 7, v5
	v_and_b32_e32 v9, 0xfffff8, v22
	v_lshlrev_b32_e32 v10, 1, v22
	s_addc_u32 s31, s19, s17
	v_lshlrev_b32_e32 v2, 3, v4
	s_add_u32 s8, s28, s8
	v_and_b32_e32 v6, 0x78, v2
	v_lshrrev_b32_e32 v7, 1, v7
	v_bfe_u32 v2, v2, 5, 2
	v_lshrrev_b32_e32 v9, 1, v9
	s_addc_u32 s9, s29, s9
	v_or_b32_e32 v7, v7, v2
	v_lshlrev_b32_e32 v166, 1, v6
	v_or_b32_e32 v2, v9, v2
	s_add_u32 s42, s8, s16
	v_lshlrev_b32_e32 v8, 6, v8
	v_and_b32_e32 v6, 48, v166
	v_lshlrev_b32_e32 v2, 9, v2
	s_addc_u32 s43, s9, s17
	v_lshlrev_b32_e32 v7, 9, v7
	v_or3_b32 v178, v2, v8, v6
	v_lshl_or_b32 v2, v5, 10, v166
	v_or3_b32 v179, v7, v8, v6
	v_lshl_add_u64 v[36:37], s[42:43], 0, v[2:3]
	global_load_dwordx4 v[6:9], v2, s[42:43]
	global_load_dwordx4 v[14:17], v2, s[30:31]
	v_add_co_u32_e32 v10, vcc, s33, v36
	v_lshl_add_u64 v[38:39], s[30:31], 0, v[2:3]
	s_nop 0
	v_addc_co_u32_e32 v11, vcc, 0, v37, vcc
	global_load_dwordx4 v[10:13], v[10:11], off
	v_add_co_u32_e32 v18, vcc, s33, v38
	v_add_u32_e32 v40, 0, v179
	s_nop 0
	v_addc_co_u32_e32 v19, vcc, 0, v39, vcc
	global_load_dwordx4 v[48:51], v[18:19], off
	v_add_co_u32_e32 v42, vcc, 0x10000, v36
	s_nop 1
	v_addc_co_u32_e32 v43, vcc, 0, v37, vcc
	v_add_co_u32_e32 v44, vcc, 0x18000, v36
	s_nop 1
	v_addc_co_u32_e32 v45, vcc, 0, v37, vcc
	v_add_co_u32_e32 v46, vcc, 0x10000, v38
	s_nop 1
	v_addc_co_u32_e32 v47, vcc, 0, v39, vcc
	v_add_co_u32_e32 v52, vcc, 0x18000, v38
	s_nop 1
	v_addc_co_u32_e32 v53, vcc, 0, v39, vcc
	v_mov_b32_e32 v54, v22
	global_load_dwordx4 v[20:23], v[42:43], off
	global_load_dwordx4 v[24:27], v[44:45], off
	global_load_dwordx4 v[28:31], v[46:47], off
	global_load_dwordx4 v[32:35], v[52:53], off
	s_waitcnt vmcnt(4)
	v_lshlrev_b32_e32 v5, 8, v5
	v_add_u32_e32 v41, 0, v178
	s_mov_b32 s8, 0x10000
	v_readfirstlane_b32 s18, v4
	s_waitcnt vmcnt(4)
	ds_write_b128 v40, v[6:9]
	v_and_b32_e32 v6, 0x70, v4
	v_bitop3_b32 v180, v166, v5, v6 bitop3:0xde
	v_add_u32_e32 v5, 0, v180
	ds_write_b128 v41, v[10:13]
	ds_write_b128 v5, v[14:17] offset:49152
	v_lshlrev_b32_e32 v5, 8, v54
	v_bitop3_b32 v181, v166, v5, v6 bitop3:0xde
	v_add_u32_e32 v5, 0, v181
	ds_write_b128 v5, v[48:51] offset:49152
	s_waitcnt lgkmcnt(0)
	s_barrier
	s_and_b32 s8, s18, 0xffffff00
	s_cmpk_lg_i32 s8, 0x100
	s_cbranch_scc1 .LBB0_628
	s_waitcnt lgkmcnt(0)
	s_barrier
